# previous stack + P2 column-tile relabelling inside each XCD half (2<->8,3<->9,10<->12,11<->13): store-heavy prompt K/V tiles go to the two-tile (fill) workgroups
# baseline (speedup 1.0000x reference)
.LBB0_157:
	v_writelane_b32 v255, s92, 13
	v_writelane_b32 v255, s86, 14
	s_cmp_lt_i32 s54, 3
	s_cselect_b64 s[40:41], -1, 0
	v_writelane_b32 v255, s87, 15
	v_writelane_b32 v255, s88, 16
	s_add_u32 s60, s18, 0x6000000
	s_addc_u32 s61, s19, 0
	v_writelane_b32 v255, s89, 17
	v_writelane_b32 v255, s94, 18
	s_add_u32 s52, s18, 0x9400000
	s_addc_u32 s53, s19, 0
	v_writelane_b32 v255, s95, 19
	v_writelane_b32 v255, s90, 20
	s_and_b64 s[0:1], s[40:41], s[6:7]
	s_andn2_b64 vcc, exec, s[0:1]
	v_writelane_b32 v255, s91, 21
	v_writelane_b32 v255, s54, 22
	v_writelane_b32 v255, s55, 23
	v_writelane_b32 v255, s96, 24
	s_nop 1
	v_writelane_b32 v255, s97, 25
	s_cbranch_vccnz .LBB0_465
	s_cmpk_lt_i32 s92, 0x280
	s_mov_b64 s[4:5], s[90:91]
	s_mov_b64 s[6:7], s[90:91]
	s_cselect_b64 s[42:43], -1, 0
	s_cmpk_gt_i32 s92, 0x27f
	v_readfirstlane_b32 s0, v0
	s_cbranch_scc1 .LBB0_160
	s_ashr_i32 s1, s92, 31
	s_lshr_b32 s1, s1, 29
	s_add_i32 s1, s92, s1
	s_ashr_i32 s2, s1, 3
	s_and_b32 s1, s1, -8
	s_sub_i32 s1, s92, s1
	s_cmp_lt_i32 s1, 0
	s_movk_i32 s3, 0x51
	s_cselect_b32 s3, s3, 0x50
	s_mul_i32 s1, s1, s3
	s_add_i32 s1, s1, s2
	s_mul_hi_i32 s2, s1, 0x66666667
	s_lshr_b32 s3, s2, 31
	s_ashr_i32 s2, s2, 6
	s_add_i32 s2, s2, s3
	s_lshl_b32 s3, s2, 3
	s_mulk_i32 s2, 0xa0
	s_sub_i32 s1, s1, s2
	s_sext_i32_i16 s2, s1
	s_bfe_u32 s2, s2, 0x3001c
	s_add_i32 s2, s1, s2
	s_sext_i32_i16 s8, s2
	s_and_b32 s2, s2, 0xfff8
	s_sub_i32 s1, s1, s2
	s_sext_i32_i16 s1, s1
	s_add_i32 s2, s3, s1
	s_ashr_i32 s20, s8, 3
	s_lshr_b32 s98, s20, 1
	s_cmp_eq_u32 s98, 1
	s_cselect_b32 s99, 6, 0
	s_cmp_eq_u32 s98, 4
	s_cselect_b32 s99, -6, s99
	s_cmp_eq_u32 s98, 5
	s_cselect_b32 s99, 2, s99
	s_cmp_eq_u32 s98, 6
	s_cselect_b32 s99, -2, s99
	s_add_i32 s20, s20, s99
	s_lshl_b32 s8, s2, 1
	s_ashr_i32 s9, s8, 31
	s_lshl_b64 s[8:9], s[8:9], 19
	s_add_u32 s10, s62, s8
	s_addc_u32 s11, s63, s9
	s_add_u32 s8, s10, 0x80000
	s_addc_u32 s9, s11, 0
	s_lshl_b32 s12, s20, 1
	s_ashr_i32 s13, s12, 31
	s_lshl_b64 s[12:13], s[12:13], 19
	s_add_u32 s84, s36, s12
	s_addc_u32 s85, s37, s13
	s_add_u32 s12, s84, 0x80000
	s_addc_u32 s13, s85, 0
	s_andn2_b64 vcc, exec, s[42:43]
	s_cbranch_vccz .LBB0_161
	s_branch .LBB0_431

.LBB0_166:
	v_readlane_b32 s6, v255, 20
	v_readlane_b32 s7, v255, 21
	s_load_dword s7, s[6:7], 0xe0
	s_add_i32 s48, s48, 1
	s_mul_i32 s3, s48, s94
	s_waitcnt lgkmcnt(0)
	s_mul_hi_u32 s6, s48, s7
	s_add_i32 s6, s6, s3
	s_mul_i32 s3, s48, s7
	s_add_u32 s86, s3, s92
	s_addc_u32 s87, s6, s95
	v_cmp_gt_i64_e32 vcc, s[86:87], v[152:153]
	v_cmp_lt_i64_e64 s[6:7], s[86:87], v[150:151]
	s_cbranch_vccnz .LBB0_168
	s_ashr_i32 s3, s86, 31
	s_lshr_b32 s3, s3, 29
	s_add_i32 s3, s86, s3
	s_ashr_i32 s21, s3, 3
	s_and_b32 s3, s3, -8
	s_sub_i32 s3, s86, s3
	s_cmp_lt_i32 s3, 0
	s_movk_i32 s35, 0x51
	s_cselect_b32 s35, s35, 0x50
	s_mul_i32 s3, s3, s35
	s_add_i32 s3, s3, s21
	s_mul_hi_i32 s21, s3, 0x66666667
	s_lshr_b32 s35, s21, 31
	s_ashr_i32 s21, s21, 6
	s_add_i32 s21, s21, s35
	s_lshl_b32 s35, s21, 3
	s_sub_i32 s40, 32, s35
	s_min_i32 s40, s40, 8
	s_abs_i32 s49, s40
	v_cvt_f32_u32_e32 v2, s49
	s_sub_i32 s76, 0, s49
	s_mulk_i32 s21, 0xa0
	s_sub_i32 s3, s3, s21
	v_rcp_iflag_f32_e32 v2, v2
	s_abs_i32 s21, s3
	s_xor_b32 s50, s3, s40
	s_ashr_i32 s50, s50, 31
	v_mul_f32_e32 v2, 0x4f7ffffe, v2
	v_cvt_u32_f32_e32 v2, v2
	s_nop 0
	v_readfirstlane_b32 s77, v2
	s_mul_i32 s76, s76, s77
	s_mul_hi_u32 s76, s77, s76
	s_add_i32 s77, s77, s76
	s_mul_hi_u32 s76, s21, s77
	s_mul_i32 s77, s76, s49
	s_sub_i32 s21, s21, s77
	s_add_i32 s78, s76, 1
	s_sub_i32 s77, s21, s49
	s_cmp_ge_u32 s21, s49
	s_cselect_b32 s76, s78, s76
	s_cselect_b32 s21, s77, s21
	s_add_i32 s77, s76, 1
	s_cmp_ge_u32 s21, s49
	s_cselect_b32 s21, s77, s76
	s_xor_b32 s21, s21, s50
	s_sub_i32 s49, s21, s50
	s_mul_i32 s21, s49, s40
	s_sub_i32 s3, s3, s21
	s_add_i32 s35, s35, s3
	s_lshr_b32 s98, s49, 1
	s_cmp_eq_u32 s98, 1
	s_cselect_b32 s99, 6, 0
	s_cmp_eq_u32 s98, 4
	s_cselect_b32 s99, -6, s99
	s_cmp_eq_u32 s98, 5
	s_cselect_b32 s99, 2, s99
	s_cmp_eq_u32 s98, 6
	s_cselect_b32 s99, -2, s99
	s_add_i32 s49, s49, s99
	s_cmp_lg_u32 s48, 1
	s_cbranch_scc1 .Lp2_noswap
	s_cmp_lt_i32 s49, 10
	s_cselect_b32 s3, 10, -10
	s_add_i32 s49, s49, s3
